# GEMM K-loop heads padded to 64-byte boundaries
# speedup vs baseline: 1.0126x; 1.0126x over previous
; template <class Epi, class Sched, bool ALIGN_EPI = false, bool SP2 = false>
; __device__ __forceinline__ void gemm_phase(PG8_LAS unsigned char* lds, const Gemm g, const Sched& S, const Epi& E, int wave_in) {
;     ...
;         const bool has_next = S.next(ui + 1, nxt);
;         const char* nA = has_next ? (const char*)g.A + (size_t)nxt.pm * tstepA : cA; const char* nB = has_next ? (const char*)g.Bt + (size_t)nxt.pn * tstep : cB;
;     ...
; #pragma unroll
;         for (int a = 0; a < 2; ++a)
; #pragma unroll
;             for (int b = 0; b < 2; ++b)
; #pragma unroll
;                 for (int m = 0; m < 4; ++m)
; #pragma unroll
;                     for (int n = 0; n < 2; ++n) acc[a][b][m][n] = (f32x4){0.f, 0.f, 0.f, 0.f};
;         cur = nxt; cA = nA; cB = nB; ++ui;
.LBB0_42:
	s_ashr_i32 s43, s42, 31
	s_lshl_b64 s[44:45], s[42:43], 20
	v_readlane_b32 s46, v253, 60
	v_readlane_b32 s47, v253, 61
	s_add_u32 s44, s46, s44
	s_addc_u32 s45, s47, s45
	s_and_b64 s[46:47], s[8:9], exec
	s_cselect_b32 s43, s45, s49
	s_cselect_b32 s67, s44, s48
	s_ashr_i32 s41, s40, 31
	s_lshl_b64 s[46:47], s[40:41], 20
	s_add_u32 s46, s54, s46
	s_addc_u32 s47, s55, s47
	s_and_b64 s[52:53], s[8:9], exec
	s_cselect_b32 s41, s47, s51
	s_cselect_b32 s68, s46, s50
	s_add_u32 s48, s48, 0x80080
	s_addc_u32 s49, s49, 0
	s_add_u32 s69, s50, 0x100
	v_mov_b32_e32 v2, 0
	s_addc_u32 s70, s51, 0
	s_mov_b32 s71, -2
	v_mov_b32_e32 v3, v2
	v_mov_b32_e32 v4, v2
	v_mov_b32_e32 v5, v2
	v_mov_b32_e32 v66, v2
	v_mov_b32_e32 v67, v2
	v_mov_b32_e32 v68, v2
	v_mov_b32_e32 v69, v2
	v_mov_b32_e32 v10, v2
	v_mov_b32_e32 v11, v2
	v_mov_b32_e32 v12, v2
	v_mov_b32_e32 v13, v2
	v_mov_b32_e32 v74, v2
	v_mov_b32_e32 v75, v2
	v_mov_b32_e32 v76, v2
	v_mov_b32_e32 v77, v2
	v_mov_b32_e32 v18, v2
	v_mov_b32_e32 v19, v2
	s_waitcnt vmcnt(0)
	v_mov_b32_e32 v20, v2
	v_mov_b32_e32 v21, v2
	v_mov_b32_e32 v82, v2
	v_mov_b32_e32 v83, v2
	v_mov_b32_e32 v84, v2
	v_mov_b32_e32 v85, v2
	v_mov_b32_e32 v26, v2
	v_mov_b32_e32 v27, v2
	v_mov_b32_e32 v28, v2
	v_mov_b32_e32 v29, v2
	v_mov_b32_e32 v90, v2
	v_mov_b32_e32 v91, v2
	v_mov_b32_e32 v92, v2
	v_mov_b32_e32 v93, v2
	v_mov_b32_e32 v6, v2
	v_mov_b32_e32 v7, v2
	v_mov_b32_e32 v8, v2
	v_mov_b32_e32 v9, v2
	v_mov_b32_e32 v70, v2
	v_mov_b32_e32 v71, v2
	v_mov_b32_e32 v72, v2
	v_mov_b32_e32 v73, v2
	v_mov_b32_e32 v14, v2
	v_mov_b32_e32 v15, v2
	v_mov_b32_e32 v16, v2
	v_mov_b32_e32 v17, v2
	v_mov_b32_e32 v78, v2
	v_mov_b32_e32 v79, v2
	v_mov_b32_e32 v80, v2
	v_mov_b32_e32 v81, v2
	v_mov_b32_e32 v22, v2
	v_mov_b32_e32 v23, v2
	v_mov_b32_e32 v24, v2
	v_mov_b32_e32 v25, v2
	v_mov_b32_e32 v86, v2
	v_mov_b32_e32 v87, v2
	v_mov_b32_e32 v88, v2
	v_mov_b32_e32 v89, v2
	v_mov_b32_e32 v30, v2
	v_mov_b32_e32 v31, v2
	v_mov_b32_e32 v32, v2
	v_mov_b32_e32 v33, v2
	v_mov_b32_e32 v94, v2
	v_mov_b32_e32 v95, v2
	v_mov_b32_e32 v96, v2
	v_mov_b32_e32 v97, v2
	v_mov_b32_e32 v34, v2
	v_mov_b32_e32 v35, v2
	v_mov_b32_e32 v36, v2
	v_mov_b32_e32 v37, v2
	v_mov_b32_e32 v98, v2
	v_mov_b32_e32 v99, v2
	v_mov_b32_e32 v100, v2
	v_mov_b32_e32 v101, v2
	v_mov_b32_e32 v42, v2
	v_mov_b32_e32 v43, v2
	v_mov_b32_e32 v44, v2
	v_mov_b32_e32 v45, v2
	v_mov_b32_e32 v138, v2
	v_mov_b32_e32 v139, v2
	v_mov_b32_e32 v140, v2
	v_mov_b32_e32 v141, v2
	v_mov_b32_e32 v50, v2
	v_mov_b32_e32 v51, v2
	v_mov_b32_e32 v52, v2
	v_mov_b32_e32 v53, v2
	v_mov_b32_e32 v146, v2
	v_mov_b32_e32 v147, v2
	v_mov_b32_e32 v148, v2
	v_mov_b32_e32 v149, v2
	v_mov_b32_e32 v58, v2
	v_mov_b32_e32 v59, v2
	v_mov_b32_e32 v60, v2
	v_mov_b32_e32 v61, v2
	v_mov_b32_e32 v134, v2
	v_mov_b32_e32 v135, v2
	v_mov_b32_e32 v136, v2
	v_mov_b32_e32 v137, v2
	v_mov_b32_e32 v38, v2
	v_mov_b32_e32 v39, v2
	v_mov_b32_e32 v40, v2
	v_mov_b32_e32 v41, v2
	v_mov_b32_e32 v102, v2
	v_mov_b32_e32 v103, v2
	v_mov_b32_e32 v104, v2
	v_mov_b32_e32 v105, v2
	v_mov_b32_e32 v46, v2
	v_mov_b32_e32 v47, v2
	v_mov_b32_e32 v48, v2
	v_mov_b32_e32 v49, v2
	v_mov_b32_e32 v142, v2
	v_mov_b32_e32 v143, v2
	v_mov_b32_e32 v144, v2
	v_mov_b32_e32 v145, v2
	v_mov_b32_e32 v54, v2
	v_mov_b32_e32 v55, v2
	v_mov_b32_e32 v56, v2
	v_mov_b32_e32 v57, v2
	v_mov_b32_e32 v150, v2
	v_mov_b32_e32 v151, v2
	v_mov_b32_e32 v152, v2
	v_mov_b32_e32 v153, v2
	v_mov_b32_e32 v62, v2
	v_mov_b32_e32 v63, v2
	v_mov_b32_e32 v64, v2
	v_mov_b32_e32 v65, v2
	v_mov_b32_e32 v154, v2
	v_mov_b32_e32 v155, v2
	v_mov_b32_e32 v156, v2
	v_mov_b32_e32 v157, v2
	s_nop 0
	s_nop 0
	s_nop 0
	s_nop 0
	s_nop 0
	s_nop 0
	s_nop 0
	s_nop 0
	s_nop 0
	s_nop 0

; template <class Epi, class Sched, bool ALIGN_EPI = false, bool SP2 = false>
; __device__ __forceinline__ void gemm_phase(PG8_LAS unsigned char* lds, const Gemm g, const Sched& S, const Epi& E, int wave_in) {
;     ...
;         const bool has_next = S.next(ui + 1, nxt);
;         const char* nA = has_next ? (const char*)g.A + (size_t)nxt.pm * tstepA : cA; const char* nB = has_next ? (const char*)g.Bt + (size_t)nxt.pn * tstep : cB;
;     ...
; #pragma unroll
;         for (int a = 0; a < 2; ++a)
; #pragma unroll
;             for (int b = 0; b < 2; ++b)
; #pragma unroll
;                 for (int m = 0; m < 4; ++m)
; #pragma unroll
;                     for (int n = 0; n < 2; ++n) acc[a][b][m][n] = (f32x4){0.f, 0.f, 0.f, 0.f};
;         cur = nxt; cA = nA; cB = nB; ++ui;
.LBB0_83:
	s_ashr_i32 s17, s16, 31
	s_lshl_b64 s[18:19], s[16:17], 20
	v_readlane_b32 s20, v253, 62
	v_readlane_b32 s21, v253, 63
	s_add_u32 s18, s20, s18
	s_addc_u32 s19, s21, s19
	s_and_b64 s[20:21], s[4:5], exec
	s_cselect_b32 s17, s19, s23
	s_cselect_b32 s42, s18, s22
	s_ashr_i32 s11, s10, 31
	s_lshl_b64 s[20:21], s[10:11], 19
	s_add_u32 s20, s28, s20
	s_addc_u32 s21, s29, s21
	s_and_b64 s[26:27], s[4:5], exec
	s_cselect_b32 s11, s21, s25
	s_cselect_b32 s43, s20, s24
	s_add_u32 s22, s22, 0x80080
	s_addc_u32 s23, s23, 0
	s_add_u32 s44, s24, 0x100
	v_mov_b32_e32 v2, 0
	s_addc_u32 s45, s25, 0
	s_mov_b32 s46, -2
	v_mov_b32_e32 v3, v2
	v_mov_b32_e32 v4, v2
	v_mov_b32_e32 v5, v2
	v_mov_b32_e32 v6, v2
	v_mov_b32_e32 v7, v2
	v_mov_b32_e32 v8, v2
	v_mov_b32_e32 v9, v2
	v_mov_b32_e32 v14, v2
	v_mov_b32_e32 v15, v2
	v_mov_b32_e32 v16, v2
	v_mov_b32_e32 v17, v2
	v_mov_b32_e32 v18, v2
	v_mov_b32_e32 v19, v2
	s_waitcnt vmcnt(0)
	v_mov_b32_e32 v20, v2
	v_mov_b32_e32 v21, v2
	v_mov_b32_e32 v30, v2
	v_mov_b32_e32 v31, v2
	v_mov_b32_e32 v32, v2
	v_mov_b32_e32 v33, v2
	v_mov_b32_e32 v34, v2
	v_mov_b32_e32 v35, v2
	v_mov_b32_e32 v36, v2
	v_mov_b32_e32 v37, v2
	v_mov_b32_e32 v46, v2
	v_mov_b32_e32 v47, v2
	v_mov_b32_e32 v48, v2
	v_mov_b32_e32 v49, v2
	v_mov_b32_e32 v50, v2
	v_mov_b32_e32 v51, v2
	v_mov_b32_e32 v52, v2
	v_mov_b32_e32 v53, v2
	v_mov_b32_e32 v10, v2
	v_mov_b32_e32 v11, v2
	v_mov_b32_e32 v12, v2
	v_mov_b32_e32 v13, v2
	v_mov_b32_e32 v22, v2
	v_mov_b32_e32 v23, v2
	v_mov_b32_e32 v24, v2
	v_mov_b32_e32 v25, v2
	v_mov_b32_e32 v26, v2
	v_mov_b32_e32 v27, v2
	v_mov_b32_e32 v28, v2
	v_mov_b32_e32 v29, v2
	v_mov_b32_e32 v38, v2
	v_mov_b32_e32 v39, v2
	v_mov_b32_e32 v40, v2
	v_mov_b32_e32 v41, v2
	v_mov_b32_e32 v42, v2
	v_mov_b32_e32 v43, v2
	v_mov_b32_e32 v44, v2
	v_mov_b32_e32 v45, v2
	v_mov_b32_e32 v54, v2
	v_mov_b32_e32 v55, v2
	v_mov_b32_e32 v56, v2
	v_mov_b32_e32 v57, v2
	v_mov_b32_e32 v58, v2
	v_mov_b32_e32 v59, v2
	v_mov_b32_e32 v60, v2
	v_mov_b32_e32 v61, v2
	v_mov_b32_e32 v62, v2
	v_mov_b32_e32 v63, v2
	v_mov_b32_e32 v64, v2
	v_mov_b32_e32 v65, v2
	v_mov_b32_e32 v66, v2
	v_mov_b32_e32 v67, v2
	v_mov_b32_e32 v68, v2
	v_mov_b32_e32 v69, v2
	v_mov_b32_e32 v70, v2
	v_mov_b32_e32 v71, v2
	v_mov_b32_e32 v72, v2
	v_mov_b32_e32 v73, v2
	v_mov_b32_e32 v78, v2
	v_mov_b32_e32 v79, v2
	v_mov_b32_e32 v80, v2
	v_mov_b32_e32 v81, v2
	v_mov_b32_e32 v82, v2
	v_mov_b32_e32 v83, v2
	v_mov_b32_e32 v84, v2
	v_mov_b32_e32 v85, v2
	v_mov_b32_e32 v94, v2
	v_mov_b32_e32 v95, v2
	v_mov_b32_e32 v96, v2
	v_mov_b32_e32 v97, v2
	v_mov_b32_e32 v98, v2
	v_mov_b32_e32 v99, v2
	v_mov_b32_e32 v100, v2
	v_mov_b32_e32 v101, v2
	v_mov_b32_e32 v110, v2
	v_mov_b32_e32 v111, v2
	v_mov_b32_e32 v112, v2
	v_mov_b32_e32 v113, v2
	v_mov_b32_e32 v114, v2
	v_mov_b32_e32 v115, v2
	v_mov_b32_e32 v116, v2
	v_mov_b32_e32 v117, v2
	v_mov_b32_e32 v74, v2
	v_mov_b32_e32 v75, v2
	v_mov_b32_e32 v76, v2
	v_mov_b32_e32 v77, v2
	v_mov_b32_e32 v86, v2
	v_mov_b32_e32 v87, v2
	v_mov_b32_e32 v88, v2
	v_mov_b32_e32 v89, v2
	v_mov_b32_e32 v90, v2
	v_mov_b32_e32 v91, v2
	v_mov_b32_e32 v92, v2
	v_mov_b32_e32 v93, v2
	v_mov_b32_e32 v102, v2
	v_mov_b32_e32 v103, v2
	v_mov_b32_e32 v104, v2
	v_mov_b32_e32 v105, v2
	v_mov_b32_e32 v106, v2
	v_mov_b32_e32 v107, v2
	v_mov_b32_e32 v108, v2
	v_mov_b32_e32 v109, v2
	v_mov_b32_e32 v118, v2
	v_mov_b32_e32 v119, v2
	v_mov_b32_e32 v120, v2
	v_mov_b32_e32 v121, v2
	v_mov_b32_e32 v122, v2
	v_mov_b32_e32 v123, v2
	v_mov_b32_e32 v124, v2
	v_mov_b32_e32 v125, v2
	v_mov_b32_e32 v126, v2
	v_mov_b32_e32 v127, v2
	v_mov_b32_e32 v128, v2
	v_mov_b32_e32 v129, v2
	s_nop 0
	s_nop 0
	s_nop 0
	s_nop 0
	s_nop 0
	s_nop 0
	s_nop 0
	s_nop 0
	s_nop 0
	s_nop 0
	s_nop 0
	s_nop 0

; template <class Epi, class Sched, bool ALIGN_EPI = false, bool SP2 = false>
; __device__ __forceinline__ void gemm_phase(PG8_LAS unsigned char* lds, const Gemm g, const Sched& S, const Epi& E, int wave_in) {
;     ...
;         const bool has_next = S.next(ui + 1, nxt);
;         const char* nA = has_next ? (const char*)g.A + (size_t)nxt.pm * tstepA : cA; const char* nB = has_next ? (const char*)g.Bt + (size_t)nxt.pn * tstep : cB;
;     ...
; #pragma unroll
;         for (int a = 0; a < 2; ++a)
; #pragma unroll
;             for (int b = 0; b < 2; ++b)
; #pragma unroll
;                 for (int m = 0; m < 4; ++m)
; #pragma unroll
;                     for (int n = 0; n < 2; ++n) acc[a][b][m][n] = (f32x4){0.f, 0.f, 0.f, 0.f};
;         cur = nxt; cA = nA; cB = nB; ++ui;
.LBB0_106:
	s_ashr_i32 s21, s20, 31
	s_lshl_b64 s[22:23], s[20:21], 20
	s_add_u32 s22, s36, s22
	s_addc_u32 s23, s37, s23
	s_and_b64 s[24:25], s[4:5], exec
	s_cselect_b32 s21, s23, s27
	s_cselect_b32 s50, s22, s26
	s_ashr_i32 s19, s18, 31
	s_lshl_b64 s[24:25], s[18:19], 18
	s_add_u32 s24, s38, s24
	s_addc_u32 s25, s39, s25
	s_and_b64 s[30:31], s[4:5], exec
	s_cselect_b32 s19, s25, s29
	s_cselect_b32 s51, s24, s28
	s_add_u32 s26, s26, 0x80080
	s_addc_u32 s27, s27, 0
	s_add_u32 s52, s28, 0x100
	v_mov_b32_e32 v2, 0
	s_addc_u32 s53, s29, 0
	s_mov_b32 s54, -2
	v_mov_b32_e32 v3, v2
	v_mov_b32_e32 v4, v2
	v_mov_b32_e32 v5, v2
	v_mov_b32_e32 v6, v2
	v_mov_b32_e32 v7, v2
	v_mov_b32_e32 v8, v2
	v_mov_b32_e32 v9, v2
	v_mov_b32_e32 v18, v2
	v_mov_b32_e32 v19, v2
	s_waitcnt vmcnt(0)
	v_mov_b32_e32 v20, v2
	v_mov_b32_e32 v21, v2
	v_mov_b32_e32 v22, v2
	v_mov_b32_e32 v23, v2
	v_mov_b32_e32 v24, v2
	v_mov_b32_e32 v25, v2
	v_mov_b32_e32 v34, v2
	v_mov_b32_e32 v35, v2
	v_mov_b32_e32 v36, v2
	v_mov_b32_e32 v37, v2
	v_mov_b32_e32 v38, v2
	v_mov_b32_e32 v39, v2
	v_mov_b32_e32 v40, v2
	v_mov_b32_e32 v41, v2
	v_mov_b32_e32 v50, v2
	v_mov_b32_e32 v51, v2
	v_mov_b32_e32 v52, v2
	v_mov_b32_e32 v53, v2
	v_mov_b32_e32 v54, v2
	v_mov_b32_e32 v55, v2
	v_mov_b32_e32 v56, v2
	v_mov_b32_e32 v57, v2
	v_mov_b32_e32 v10, v2
	v_mov_b32_e32 v11, v2
	v_mov_b32_e32 v12, v2
	v_mov_b32_e32 v13, v2
	v_mov_b32_e32 v14, v2
	v_mov_b32_e32 v15, v2
	v_mov_b32_e32 v16, v2
	v_mov_b32_e32 v17, v2
	v_mov_b32_e32 v26, v2
	v_mov_b32_e32 v27, v2
	v_mov_b32_e32 v28, v2
	v_mov_b32_e32 v29, v2
	v_mov_b32_e32 v30, v2
	v_mov_b32_e32 v31, v2
	v_mov_b32_e32 v32, v2
	v_mov_b32_e32 v33, v2
	v_mov_b32_e32 v42, v2
	v_mov_b32_e32 v43, v2
	v_mov_b32_e32 v44, v2
	v_mov_b32_e32 v45, v2
	v_mov_b32_e32 v46, v2
	v_mov_b32_e32 v47, v2
	v_mov_b32_e32 v48, v2
	v_mov_b32_e32 v49, v2
	v_mov_b32_e32 v58, v2
	v_mov_b32_e32 v59, v2
	v_mov_b32_e32 v60, v2
	v_mov_b32_e32 v61, v2
	v_mov_b32_e32 v62, v2
	v_mov_b32_e32 v63, v2
	v_mov_b32_e32 v64, v2
	v_mov_b32_e32 v65, v2
	v_mov_b32_e32 v66, v2
	v_mov_b32_e32 v67, v2
	v_mov_b32_e32 v68, v2
	v_mov_b32_e32 v69, v2
	v_mov_b32_e32 v70, v2
	v_mov_b32_e32 v71, v2
	v_mov_b32_e32 v72, v2
	v_mov_b32_e32 v73, v2
	v_mov_b32_e32 v82, v2
	v_mov_b32_e32 v83, v2
	v_mov_b32_e32 v84, v2
	v_mov_b32_e32 v85, v2
	v_mov_b32_e32 v86, v2
	v_mov_b32_e32 v87, v2
	v_mov_b32_e32 v88, v2
	v_mov_b32_e32 v89, v2
	v_mov_b32_e32 v98, v2
	v_mov_b32_e32 v99, v2
	v_mov_b32_e32 v100, v2
	v_mov_b32_e32 v101, v2
	v_mov_b32_e32 v102, v2
	v_mov_b32_e32 v103, v2
	v_mov_b32_e32 v104, v2
	v_mov_b32_e32 v105, v2
	v_mov_b32_e32 v114, v2
	v_mov_b32_e32 v115, v2
	v_mov_b32_e32 v116, v2
	v_mov_b32_e32 v117, v2
	v_mov_b32_e32 v118, v2
	v_mov_b32_e32 v119, v2
	v_mov_b32_e32 v120, v2
	v_mov_b32_e32 v121, v2
	v_mov_b32_e32 v74, v2
	v_mov_b32_e32 v75, v2
	v_mov_b32_e32 v76, v2
	v_mov_b32_e32 v77, v2
	v_mov_b32_e32 v78, v2
	v_mov_b32_e32 v79, v2
	v_mov_b32_e32 v80, v2
	v_mov_b32_e32 v81, v2
	v_mov_b32_e32 v90, v2
	v_mov_b32_e32 v91, v2
	v_mov_b32_e32 v92, v2
	v_mov_b32_e32 v93, v2
	v_mov_b32_e32 v94, v2
	v_mov_b32_e32 v95, v2
	v_mov_b32_e32 v96, v2
	v_mov_b32_e32 v97, v2
	v_mov_b32_e32 v106, v2
	v_mov_b32_e32 v107, v2
	v_mov_b32_e32 v108, v2
	v_mov_b32_e32 v109, v2
	v_mov_b32_e32 v110, v2
	v_mov_b32_e32 v111, v2
	v_mov_b32_e32 v112, v2
	v_mov_b32_e32 v113, v2
	v_mov_b32_e32 v122, v2
	v_mov_b32_e32 v123, v2
	v_mov_b32_e32 v124, v2
	v_mov_b32_e32 v125, v2
	v_mov_b32_e32 v126, v2
	v_mov_b32_e32 v127, v2
	v_mov_b32_e32 v128, v2
	v_mov_b32_e32 v129, v2
	s_nop 0
	s_nop 0
	s_nop 0

; template <class Epi, class Sched, bool ALIGN_EPI = false, bool SP2 = false>
; __device__ __forceinline__ void gemm_phase(PG8_LAS unsigned char* lds, const Gemm g, const Sched& S, const Epi& E, int wave_in) {
;     ...
;         const bool has_next = S.next(ui + 1, nxt);
;         const char* nA = has_next ? (const char*)g.A + (size_t)nxt.pm * tstepA : cA; const char* nB = has_next ? (const char*)g.Bt + (size_t)nxt.pn * tstep : cB;
;     ...
; #pragma unroll
;         for (int a = 0; a < 2; ++a)
; #pragma unroll
;             for (int b = 0; b < 2; ++b)
; #pragma unroll
;                 for (int m = 0; m < 4; ++m)
; #pragma unroll
;                     for (int n = 0; n < 2; ++n) acc[a][b][m][n] = (f32x4){0.f, 0.f, 0.f, 0.f};
;         cur = nxt; cA = nA; cB = nB; ++ui;
.LBB0_127:
	s_ashr_i32 s17, s16, 31
	s_lshl_b64 s[18:19], s[16:17], 18
	s_add_u32 s18, s14, s18
	s_addc_u32 s19, s15, s19
	s_and_b64 s[20:21], s[0:1], exec
	s_cselect_b32 s17, s19, s23
	s_cselect_b32 s42, s18, s22
	s_ashr_i32 s11, s10, 31
	s_lshl_b64 s[20:21], s[10:11], 18
	s_add_u32 s20, s28, s20
	s_addc_u32 s21, s29, s21
	s_and_b64 s[26:27], s[0:1], exec
	s_cselect_b32 s11, s21, s25
	s_cselect_b32 s43, s20, s24
	s_add_u32 s22, s22, 0x20080
	s_addc_u32 s23, s23, 0
	s_add_u32 s44, s24, 0x100
	v_mov_b32_e32 v2, 0
	s_addc_u32 s45, s25, 0
	s_mov_b32 s46, -2
	v_mov_b32_e32 v3, v2
	v_mov_b32_e32 v4, v2
	v_mov_b32_e32 v5, v2
	v_mov_b32_e32 v6, v2
	v_mov_b32_e32 v7, v2
	v_mov_b32_e32 v8, v2
	v_mov_b32_e32 v9, v2
	v_mov_b32_e32 v18, v2
	v_mov_b32_e32 v19, v2
	s_waitcnt vmcnt(0)
	v_mov_b32_e32 v20, v2
	v_mov_b32_e32 v21, v2
	v_mov_b32_e32 v22, v2
	v_mov_b32_e32 v23, v2
	v_mov_b32_e32 v24, v2
	v_mov_b32_e32 v25, v2
	v_mov_b32_e32 v34, v2
	v_mov_b32_e32 v35, v2
	v_mov_b32_e32 v36, v2
	v_mov_b32_e32 v37, v2
	v_mov_b32_e32 v38, v2
	v_mov_b32_e32 v39, v2
	v_mov_b32_e32 v40, v2
	v_mov_b32_e32 v41, v2
	v_mov_b32_e32 v50, v2
	v_mov_b32_e32 v51, v2
	v_mov_b32_e32 v52, v2
	v_mov_b32_e32 v53, v2
	v_mov_b32_e32 v54, v2
	v_mov_b32_e32 v55, v2
	v_mov_b32_e32 v56, v2
	v_mov_b32_e32 v57, v2
	v_mov_b32_e32 v10, v2
	v_mov_b32_e32 v11, v2
	v_mov_b32_e32 v12, v2
	v_mov_b32_e32 v13, v2
	v_mov_b32_e32 v14, v2
	v_mov_b32_e32 v15, v2
	v_mov_b32_e32 v16, v2
	v_mov_b32_e32 v17, v2
	v_mov_b32_e32 v26, v2
	v_mov_b32_e32 v27, v2
	v_mov_b32_e32 v28, v2
	v_mov_b32_e32 v29, v2
	v_mov_b32_e32 v30, v2
	v_mov_b32_e32 v31, v2
	v_mov_b32_e32 v32, v2
	v_mov_b32_e32 v33, v2
	v_mov_b32_e32 v42, v2
	v_mov_b32_e32 v43, v2
	v_mov_b32_e32 v44, v2
	v_mov_b32_e32 v45, v2
	v_mov_b32_e32 v46, v2
	v_mov_b32_e32 v47, v2
	v_mov_b32_e32 v48, v2
	v_mov_b32_e32 v49, v2
	v_mov_b32_e32 v74, v2
	v_mov_b32_e32 v75, v2
	v_mov_b32_e32 v76, v2
	v_mov_b32_e32 v77, v2
	v_mov_b32_e32 v78, v2
	v_mov_b32_e32 v79, v2
	v_mov_b32_e32 v80, v2
	v_mov_b32_e32 v81, v2
	v_mov_b32_e32 v82, v2
	v_mov_b32_e32 v83, v2
	v_mov_b32_e32 v84, v2
	v_mov_b32_e32 v85, v2
	v_mov_b32_e32 v86, v2
	v_mov_b32_e32 v87, v2
	v_mov_b32_e32 v88, v2
	v_mov_b32_e32 v89, v2
	v_mov_b32_e32 v98, v2
	v_mov_b32_e32 v99, v2
	v_mov_b32_e32 v100, v2
	v_mov_b32_e32 v101, v2
	v_mov_b32_e32 v102, v2
	v_mov_b32_e32 v103, v2
	v_mov_b32_e32 v104, v2
	v_mov_b32_e32 v105, v2
	v_mov_b32_e32 v114, v2
	v_mov_b32_e32 v115, v2
	v_mov_b32_e32 v116, v2
	v_mov_b32_e32 v117, v2
	v_mov_b32_e32 v118, v2
	v_mov_b32_e32 v119, v2
	v_mov_b32_e32 v120, v2
	v_mov_b32_e32 v121, v2
	v_mov_b32_e32 v130, v2
	v_mov_b32_e32 v131, v2
	v_mov_b32_e32 v132, v2
	v_mov_b32_e32 v133, v2
	v_mov_b32_e32 v134, v2
	v_mov_b32_e32 v135, v2
	v_mov_b32_e32 v136, v2
	v_mov_b32_e32 v137, v2
	v_mov_b32_e32 v90, v2
	v_mov_b32_e32 v91, v2
	v_mov_b32_e32 v92, v2
	v_mov_b32_e32 v93, v2
	v_mov_b32_e32 v94, v2
	v_mov_b32_e32 v95, v2
	v_mov_b32_e32 v96, v2
	v_mov_b32_e32 v97, v2
	v_mov_b32_e32 v106, v2
	v_mov_b32_e32 v107, v2
	v_mov_b32_e32 v108, v2
	v_mov_b32_e32 v109, v2
	v_mov_b32_e32 v110, v2
	v_mov_b32_e32 v111, v2
	v_mov_b32_e32 v112, v2
	v_mov_b32_e32 v113, v2
	v_mov_b32_e32 v122, v2
	v_mov_b32_e32 v123, v2
	v_mov_b32_e32 v124, v2
	v_mov_b32_e32 v125, v2
	v_mov_b32_e32 v126, v2
	v_mov_b32_e32 v127, v2
	v_mov_b32_e32 v128, v2
	v_mov_b32_e32 v129, v2
	v_mov_b32_e32 v138, v2
	v_mov_b32_e32 v139, v2
	v_mov_b32_e32 v140, v2
	v_mov_b32_e32 v141, v2
	v_mov_b32_e32 v142, v2
	v_mov_b32_e32 v143, v2
	v_mov_b32_e32 v144, v2
	v_mov_b32_e32 v145, v2
	s_nop 0
	s_nop 0
	s_nop 0
	s_nop 0
	s_nop 0
	s_nop 0
	s_nop 0
	s_nop 0
	s_nop 0

; template <class Epi, class Sched, bool ALIGN_EPI = false, bool SP2 = false>
; __device__ __forceinline__ void gemm_phase(PG8_LAS unsigned char* lds, const Gemm g, const Sched& S, const Epi& E, int wave_in) {
;     ...
;         const bool has_next = S.next(ui + 1, nxt);
;         const char* nA = has_next ? (const char*)g.A + (size_t)nxt.pm * tstepA : cA; const char* nB = has_next ? (const char*)g.Bt + (size_t)nxt.pn * tstep : cB;
;     ...
; #pragma unroll
;         for (int a = 0; a < 2; ++a)
; #pragma unroll
;             for (int b = 0; b < 2; ++b)
; #pragma unroll
;                 for (int m = 0; m < 4; ++m)
; #pragma unroll
;                     for (int n = 0; n < 2; ++n) acc[a][b][m][n] = (f32x4){0.f, 0.f, 0.f, 0.f};
;         cur = nxt; cA = nA; cB = nB; ++ui;
.LBB0_276:
	s_ashr_i32 s19, s18, 31
	s_lshl_b64 s[4:5], s[18:19], 20
	v_readlane_b32 s20, v253, 60
	v_readlane_b32 s21, v253, 61
	s_add_u32 s20, s20, s4
	s_load_dwordx2 s[22:23], s[82:83], 0xf8
	s_addc_u32 s21, s21, s5
	s_and_b64 s[4:5], s[6:7], exec
	s_cselect_b32 s19, s21, s1
	s_cselect_b32 s36, s20, s0
	s_ashr_i32 s17, s16, 31
	s_lshl_b64 s[4:5], s[16:17], 20
	s_waitcnt lgkmcnt(0)
	s_add_u32 s22, s22, s4
	s_addc_u32 s23, s23, s5
	s_and_b64 s[4:5], s[6:7], exec
	s_cselect_b32 s17, s23, s3
	s_cselect_b32 s37, s22, s2
	s_add_u32 s0, s0, 0x80080
	s_addc_u32 s1, s1, 0
	s_add_u32 s38, s2, 0x100
	v_mov_b32_e32 v2, 0
	s_addc_u32 s39, s3, 0
	s_mov_b32 s40, -2
	v_mov_b32_e32 v3, v2
	v_mov_b32_e32 v4, v2
	v_mov_b32_e32 v5, v2
	v_mov_b32_e32 v6, v2
	v_mov_b32_e32 v7, v2
	v_mov_b32_e32 v8, v2
	v_mov_b32_e32 v9, v2
	v_mov_b32_e32 v18, v2
	v_mov_b32_e32 v19, v2
	s_waitcnt vmcnt(0)
	v_mov_b32_e32 v20, v2
	v_mov_b32_e32 v21, v2
	v_mov_b32_e32 v22, v2
	v_mov_b32_e32 v23, v2
	v_mov_b32_e32 v24, v2
	v_mov_b32_e32 v25, v2
	v_mov_b32_e32 v50, v2
	v_mov_b32_e32 v51, v2
	v_mov_b32_e32 v52, v2
	v_mov_b32_e32 v53, v2
	v_mov_b32_e32 v54, v2
	v_mov_b32_e32 v55, v2
	v_mov_b32_e32 v56, v2
	v_mov_b32_e32 v57, v2
	v_mov_b32_e32 v66, v2
	v_mov_b32_e32 v67, v2
	v_mov_b32_e32 v68, v2
	v_mov_b32_e32 v69, v2
	v_mov_b32_e32 v70, v2
	v_mov_b32_e32 v71, v2
	v_mov_b32_e32 v72, v2
	v_mov_b32_e32 v73, v2
	v_mov_b32_e32 v10, v2
	v_mov_b32_e32 v11, v2
	v_mov_b32_e32 v12, v2
	v_mov_b32_e32 v13, v2
	v_mov_b32_e32 v14, v2
	v_mov_b32_e32 v15, v2
	v_mov_b32_e32 v16, v2
	v_mov_b32_e32 v17, v2
	v_mov_b32_e32 v34, v2
	v_mov_b32_e32 v35, v2
	v_mov_b32_e32 v36, v2
	v_mov_b32_e32 v37, v2
	v_mov_b32_e32 v38, v2
	v_mov_b32_e32 v39, v2
	v_mov_b32_e32 v40, v2
	v_mov_b32_e32 v41, v2
	v_mov_b32_e32 v58, v2
	v_mov_b32_e32 v59, v2
	v_mov_b32_e32 v60, v2
	v_mov_b32_e32 v61, v2
	v_mov_b32_e32 v62, v2
	v_mov_b32_e32 v63, v2
	v_mov_b32_e32 v64, v2
	v_mov_b32_e32 v65, v2
	v_mov_b32_e32 v74, v2
	v_mov_b32_e32 v75, v2
	v_mov_b32_e32 v76, v2
	v_mov_b32_e32 v77, v2
	v_mov_b32_e32 v78, v2
	v_mov_b32_e32 v79, v2
	v_mov_b32_e32 v80, v2
	v_mov_b32_e32 v81, v2
	v_mov_b32_e32 v82, v2
	v_mov_b32_e32 v83, v2
	v_mov_b32_e32 v84, v2
	v_mov_b32_e32 v85, v2
	v_mov_b32_e32 v86, v2
	v_mov_b32_e32 v87, v2
	v_mov_b32_e32 v88, v2
	v_mov_b32_e32 v89, v2
	v_mov_b32_e32 v98, v2
	v_mov_b32_e32 v99, v2
	v_mov_b32_e32 v100, v2
	v_mov_b32_e32 v101, v2
	v_mov_b32_e32 v102, v2
	v_mov_b32_e32 v103, v2
	v_mov_b32_e32 v104, v2
	v_mov_b32_e32 v105, v2
	v_mov_b32_e32 v114, v2
	v_mov_b32_e32 v115, v2
	v_mov_b32_e32 v116, v2
	v_mov_b32_e32 v117, v2
	v_mov_b32_e32 v118, v2
	v_mov_b32_e32 v119, v2
	v_mov_b32_e32 v120, v2
	v_mov_b32_e32 v121, v2
	v_mov_b32_e32 v130, v2
	v_mov_b32_e32 v131, v2
	v_mov_b32_e32 v132, v2
	v_mov_b32_e32 v133, v2
	v_mov_b32_e32 v134, v2
	v_mov_b32_e32 v135, v2
	v_mov_b32_e32 v136, v2
	v_mov_b32_e32 v137, v2
	v_mov_b32_e32 v90, v2
	v_mov_b32_e32 v91, v2
	v_mov_b32_e32 v92, v2
	v_mov_b32_e32 v93, v2
	v_mov_b32_e32 v94, v2
	v_mov_b32_e32 v95, v2
	v_mov_b32_e32 v96, v2
	v_mov_b32_e32 v97, v2
	v_mov_b32_e32 v106, v2
	v_mov_b32_e32 v107, v2
	v_mov_b32_e32 v108, v2
	v_mov_b32_e32 v109, v2
	v_mov_b32_e32 v110, v2
	v_mov_b32_e32 v111, v2
	v_mov_b32_e32 v112, v2
	v_mov_b32_e32 v113, v2
	v_mov_b32_e32 v122, v2
	v_mov_b32_e32 v123, v2
	v_mov_b32_e32 v124, v2
	v_mov_b32_e32 v125, v2
	v_mov_b32_e32 v126, v2
	v_mov_b32_e32 v127, v2
	v_mov_b32_e32 v128, v2
	v_mov_b32_e32 v129, v2
	v_mov_b32_e32 v138, v2
	v_mov_b32_e32 v139, v2
	v_mov_b32_e32 v140, v2
	v_mov_b32_e32 v141, v2
	v_mov_b32_e32 v142, v2
	v_mov_b32_e32 v143, v2
	v_mov_b32_e32 v144, v2
	v_mov_b32_e32 v145, v2
	s_nop 0
	s_nop 0
	s_nop 0
	s_nop 0
	s_nop 0
	s_nop 0
	s_nop 0
	s_nop 0
	s_nop 0
	s_nop 0

; template <class Epi, class Sched, bool ALIGN_EPI = false, bool SP2 = false>
; __device__ __forceinline__ void gemm_phase(PG8_LAS unsigned char* lds, const Gemm g, const Sched& S, const Epi& E, int wave_in) {
;     ...
; #pragma unroll
;         for (int a = 0; a < 2; ++a)
; #pragma unroll
;             for (int b = 0; b < 2; ++b)
; #pragma unroll
;                 for (int m = 0; m < 4; ++m)
; #pragma unroll
;                     for (int n = 0; n < 2; ++n) acc[a][b][m][n] = (f32x4){0.f, 0.f, 0.f, 0.f};
;         cur = nxt; cA = nA; cB = nB; ++ui;
.LBB0_403:
	s_add_u32 s4, s24, 0x80
	s_addc_u32 s5, s25, 0
	s_add_u32 s24, s6, 0x100
	v_mov_b32_e32 v2, 0
	s_addc_u32 s25, s7, 0
	s_mov_b32 s6, 0
	v_mov_b32_e32 v3, v2
	v_mov_b32_e32 v4, v2
	v_mov_b32_e32 v5, v2
	v_mov_b32_e32 v6, v2
	s_waitcnt lgkmcnt(0)
	v_mov_b32_e32 v7, v2
	v_mov_b32_e32 v8, v2
	v_mov_b32_e32 v9, v2
	v_mov_b32_e32 v18, v2
	v_mov_b32_e32 v19, v2
	v_mov_b32_e32 v20, v2
	v_mov_b32_e32 v21, v2
	v_mov_b32_e32 v22, v2
	v_mov_b32_e32 v23, v2
	s_waitcnt vmcnt(0)
	v_mov_b32_e32 v24, v2
	v_mov_b32_e32 v25, v2
	v_mov_b32_e32 v34, v2
	v_mov_b32_e32 v35, v2
	v_mov_b32_e32 v36, v2
	v_mov_b32_e32 v37, v2
	v_mov_b32_e32 v38, v2
	v_mov_b32_e32 v39, v2
	v_mov_b32_e32 v40, v2
	v_mov_b32_e32 v41, v2
	v_mov_b32_e32 v50, v2
	v_mov_b32_e32 v51, v2
	v_mov_b32_e32 v52, v2
	v_mov_b32_e32 v53, v2
	v_mov_b32_e32 v54, v2
	v_mov_b32_e32 v55, v2
	v_mov_b32_e32 v56, v2
	v_mov_b32_e32 v57, v2
	v_mov_b32_e32 v10, v2
	v_mov_b32_e32 v11, v2
	v_mov_b32_e32 v12, v2
	v_mov_b32_e32 v13, v2
	v_mov_b32_e32 v14, v2
	v_mov_b32_e32 v15, v2
	v_mov_b32_e32 v16, v2
	v_mov_b32_e32 v17, v2
	v_mov_b32_e32 v26, v2
	v_mov_b32_e32 v27, v2
	v_mov_b32_e32 v28, v2
	v_mov_b32_e32 v29, v2
	v_mov_b32_e32 v30, v2
	v_mov_b32_e32 v31, v2
	v_mov_b32_e32 v32, v2
	v_mov_b32_e32 v33, v2
	v_mov_b32_e32 v42, v2
	v_mov_b32_e32 v43, v2
	v_mov_b32_e32 v44, v2
	v_mov_b32_e32 v45, v2
	v_mov_b32_e32 v46, v2
	v_mov_b32_e32 v47, v2
	v_mov_b32_e32 v48, v2
	v_mov_b32_e32 v49, v2
	v_mov_b32_e32 v58, v2
	v_mov_b32_e32 v59, v2
	v_mov_b32_e32 v60, v2
	v_mov_b32_e32 v61, v2
	v_mov_b32_e32 v62, v2
	v_mov_b32_e32 v63, v2
	v_mov_b32_e32 v64, v2
	v_mov_b32_e32 v65, v2
	v_mov_b32_e32 v66, v2
	v_mov_b32_e32 v67, v2
	v_mov_b32_e32 v68, v2
	v_mov_b32_e32 v69, v2
	v_mov_b32_e32 v70, v2
	v_mov_b32_e32 v71, v2
	v_mov_b32_e32 v72, v2
	v_mov_b32_e32 v73, v2
	v_mov_b32_e32 v82, v2
	v_mov_b32_e32 v83, v2
	v_mov_b32_e32 v84, v2
	v_mov_b32_e32 v85, v2
	v_mov_b32_e32 v86, v2
	v_mov_b32_e32 v87, v2
	v_mov_b32_e32 v88, v2
	v_mov_b32_e32 v89, v2
	v_mov_b32_e32 v98, v2
	v_mov_b32_e32 v99, v2
	v_mov_b32_e32 v100, v2
	v_mov_b32_e32 v101, v2
	v_mov_b32_e32 v102, v2
	v_mov_b32_e32 v103, v2
	v_mov_b32_e32 v104, v2
	v_mov_b32_e32 v105, v2
	v_mov_b32_e32 v114, v2
	v_mov_b32_e32 v115, v2
	v_mov_b32_e32 v116, v2
	v_mov_b32_e32 v117, v2
	v_mov_b32_e32 v118, v2
	v_mov_b32_e32 v119, v2
	v_mov_b32_e32 v120, v2
	v_mov_b32_e32 v121, v2
	v_mov_b32_e32 v74, v2
	v_mov_b32_e32 v75, v2
	v_mov_b32_e32 v76, v2
	v_mov_b32_e32 v77, v2
	v_mov_b32_e32 v78, v2
	v_mov_b32_e32 v79, v2
	v_mov_b32_e32 v80, v2
	v_mov_b32_e32 v81, v2
	v_mov_b32_e32 v90, v2
	v_mov_b32_e32 v91, v2
	v_mov_b32_e32 v92, v2
	v_mov_b32_e32 v93, v2
	v_mov_b32_e32 v94, v2
	v_mov_b32_e32 v95, v2
	v_mov_b32_e32 v96, v2
	v_mov_b32_e32 v97, v2
	v_mov_b32_e32 v106, v2
	v_mov_b32_e32 v107, v2
	v_mov_b32_e32 v108, v2
	v_mov_b32_e32 v109, v2
	v_mov_b32_e32 v110, v2
	v_mov_b32_e32 v111, v2
	v_mov_b32_e32 v112, v2
	v_mov_b32_e32 v113, v2
	v_mov_b32_e32 v122, v2
	v_mov_b32_e32 v123, v2
	v_mov_b32_e32 v124, v2
	v_mov_b32_e32 v125, v2
	v_mov_b32_e32 v126, v2
	v_mov_b32_e32 v127, v2
	v_mov_b32_e32 v128, v2
	v_mov_b32_e32 v129, v2
	s_nop 0
	s_nop 0
	s_nop 0
	s_nop 0
	s_nop 0
	s_nop 0
	s_nop 0
	s_nop 0
	s_nop 0
